# baseline (speedup 1.0000x reference)
; #define LAS __attribute__((address_space(3)))
; DI u32x4 pack8(const f32x4 a, const f32x4 b) { u32x4 w; w.x = cvt_pk_bf16(a[0], a[1]); w.y = cvt_pk_bf16(a[2], a[3]); w.z = cvt_pk_bf16(b[0], b[1]); w.w = cvt_pk_bf16(b[2], b[3]); return w; }
;     DI void operator()(const pg8::f32x4 (&acc)[2][2][4][2], const pg8::Unit& u, int wr, int wc, int fr, int fq) const {
;     ...
; #pragma unroll
;         for (int ai = 0; ai < 2; ++ai)
; #pragma unroll
;             for (int mm = 0; mm < 2; ++mm) {
;                 const int m = mm * 3;
;                 const bool sel = mm == 0 ? (fr < 2) : (fr >= 14);
;                 if (sel) {
;                     const int r = u.pm * 256 + ai * 128 + wr * 64 + m * 16 + fr, slot = mm == 0 ? fr : fr - 12;
;                     bf16_t* rp = RAW + ((size_t)(r >> 6) * 4 + slot) * UPC + j0;
;                     *(u32x4*)rp = pack8(acc[ai][0][m][0], acc[ai][0][m][1]); *(u32x4*)(rp + DFF) = pack8(acc[ai][1][m][0], acc[ai][1][m][1]);
;                     if (mm == 1 && (r & 2047) >= SEQ - 2) { float* fo = cp + (size_t)((r >> 11) * 2 + ((r & 2047) - (SEQ - 2))) * UPC + j0;
;                         *(f32x4*)fo = acc[ai][0][m][0]; *(f32x4*)(fo + 4) = acc[ai][0][m][1]; *(f32x4*)(fo + DFF) = acc[ai][1][m][0]; *(f32x4*)(fo + DFF + 4) = acc[ai][1][m][1]; }
;                 }
;     ...
;             LAS float* Wl = (LAS float*)(lds + CW_OFF);
; #pragma unroll
;             for (int i = 0; i < 2; ++i) {
;                 const int idx = tid + 512 * i, kind = idx >> 7, c = idx & 127, hv = kind >> 2, kk = kind & 3;
;                 Wl[idx] = kk < 3 ? cw[(size_t)kk * UPC + hv * DFF + u.pn * 128 + c] : cb[hv * DFF + u.pn * 128 + c];
.LBB0_817:
	s_mov_b32 s24, s79
	v_mov_b32_e32 v180, v246
	s_mov_b32 s6, s73
	v_mov_b32_e32 v129, v249
	s_lshl_b32 s62, s38, 7
	s_lshl_b32 s7, s24, 5
	s_add_i32 s14, s7, s62
	v_lshlrev_b32_e32 v128, 3, v129
	v_add_u32_e32 v178, s14, v128
	v_readlane_b32 s34, v253, 27
	v_readlane_b32 s66, v253, 29
	s_mov_b64 s[14:15], -1
	s_cmp_eq_u32 s40, 32
	v_ashrrev_i32_e32 v179, 31, v178
	v_readlane_b32 s35, v253, 28
	v_readlane_b32 s67, v253, 30
	s_cbranch_scc1 .LBB0_842
	s_lshl_b32 s100, s6, 8
	s_lshl_b32 s101, s24, 6
	s_add_i32 s100, s100, s101
	v_lshlrev_b32_e32 v234, 4, v129
	v_add3_u32 v234, s100, v180, v234
	v_bfe_u32 v236, v234, 7, 2
	v_cmp_eq_u32_e32 vcc, 3, v236
	v_mul_u32_u24_e32 v236, 0x2c00, v236
	v_lshlrev_b32_e32 v160, 2, v236
	v_and_b32_e32 v238, 0x7f, v234
	s_ashr_i32 s63, s62, 31
	v_lshl_add_u64 v[236:237], s[0:1], 0, v[160:161]
	v_or_b32_e32 v239, s62, v238
	v_lshl_add_u64 v[236:237], s[62:63], 2, v[236:237]
	v_lshlrev_b32_e32 v160, 2, v238
	v_lshl_add_u64 v[236:237], v[236:237], 0, v[160:161]
	v_ashrrev_i32_e32 v238, 9, v234
	v_cndmask_b32_e32 v240, 0, v239, vcc
	s_movk_i32 s100, 0x1600
	v_mov_b32_e32 v239, s45
	v_mad_i32_i24 v238, v238, s100, v240
	v_cndmask_b32_e32 v237, v237, v239, vcc
	v_mov_b32_e32 v239, s44
	v_cndmask_b32_e32 v236, v236, v239, vcc
	v_ashrrev_i32_e32 v239, 31, v238
	v_add_u32_e32 v234, 0x200, v234
	v_lshl_add_u64 v[238:239], v[238:239], 2, v[236:237]
	v_ashrrev_i32_e32 v234, 9, v234
	global_load_dword v241, v[238:239], off
	v_mad_i32_i24 v238, v234, s100, v240
	v_ashrrev_i32_e32 v239, 31, v238
	v_lshl_add_u64 v[236:237], v[238:239], 2, v[236:237]
	global_load_dword v235, v[236:237], off
	s_lshl_b32 s14, s40, 8
	s_lshl_b32 s15, s6, 6
	s_add_i32 s15, s15, s14
	v_cmp_gt_i32_e64 s[38:39], 2, v180
	v_add_u32_e32 v164, s15, v180
	v_ashrrev_i32_e32 v181, 31, v180
	s_and_saveexec_b64 s[40:41], s[38:39]
	s_cbranch_execz .LBB0_820
	v_ashrrev_i32_e32 v130, 6, v164
	v_readlane_b32 s14, v253, 35
	v_ashrrev_i32_e32 v131, 31, v130
	v_readlane_b32 s15, v253, 36
	v_lshl_add_u64 v[130:131], v[130:131], 2, v[180:181]
	s_nop 0
	v_mov_b64_e32 v[132:133], s[14:15]
	v_mad_u64_u32 v[132:133], s[14:15], v130, s86, v[132:133]
	v_mad_i32_i24 v133, v131, s86, v133
	v_lshl_add_u64 v[134:135], v[178:179], 1, v[132:133]
	v_cvt_pk_bf16_f32 v130, v124, v125
	v_cvt_pk_bf16_f32 v131, v126, v127
	v_cvt_pk_bf16_f32 v132, v120, v121
	v_cvt_pk_bf16_f32 v133, v122, v123
	global_store_dwordx4 v[134:135], v[130:133], off
	v_add_co_u32_e32 v134, vcc, 0x2000, v134
	s_nop 0
	v_cvt_pk_bf16_f32 v130, v116, v117
	v_cvt_pk_bf16_f32 v131, v118, v119
	v_cvt_pk_bf16_f32 v132, v112, v113
	v_cvt_pk_bf16_f32 v133, v114, v115
	s_nop 0
	v_addc_co_u32_e32 v135, vcc, 0, v135, vcc
	global_store_dwordx4 v[134:135], v[130:133], off offset:3072

; #define LAS __attribute__((address_space(3)))
;     DI void operator()(const pg8::f32x4 (&acc)[2][2][4][2], const pg8::Unit& u, int wr, int wc, int fr, int fq) const {
;     ...
;         {
;             LAS float* Wl = (LAS float*)(lds + CW_OFF);
; #pragma unroll
;             for (int i = 0; i < 2; ++i) {
;                 const int idx = tid + 512 * i, kind = idx >> 7, c = idx & 127, hv = kind >> 2, kk = kind & 3;
;                 Wl[idx] = kk < 3 ? cw[(size_t)kk * UPC + hv * DFF + u.pn * 128 + c] : cb[hv * DFF + u.pn * 128 + c];
;             }
;             asm volatile("s_waitcnt lgkmcnt(0)" ::: "memory"); __builtin_amdgcn_s_barrier(); asm volatile("" ::: "memory");
;         }
;         const LAS float* wl = (const LAS float*)(lds + CW_OFF) + wc * 32 + 8 * fq;
; #pragma unroll
;         for (int q = 0; q < 2; ++q) {
;             const f32x4 kg0 = *(const LAS f32x4*)(wl + 4 * q), kg1 = *(const LAS f32x4*)(wl + 128 + 4 * q), kg2 = *(const LAS f32x4*)(wl + 256 + 4 * q), bg = *(const LAS f32x4*)(wl + 384 + 4 * q);
;             const f32x4 kv0 = *(const LAS f32x4*)(wl + 512 + 4 * q), kv1 = *(const LAS f32x4*)(wl + 640 + 4 * q), kv2 = *(const LAS f32x4*)(wl + 768 + 4 * q), bv = *(const LAS f32x4*)(wl + 896 + 4 * q);
.LBB0_828:
	s_or_b64 exec, exec, s[38:39]
	s_lshl_b32 s14, s6, 8
	s_lshl_b32 s15, s24, 6
	v_lshlrev_b32_e32 v129, 4, v129
	s_add_i32 s14, s14, s15
	v_add3_u32 v129, s14, v180, v129
	v_bfe_u32 v130, v129, 7, 2
	v_cmp_eq_u32_e32 vcc, 3, v130
	v_mul_u32_u24_e32 v130, 0x2c00, v130
	v_lshlrev_b32_e32 v160, 2, v130
	v_and_b32_e32 v132, 0x7f, v129
	s_ashr_i32 s63, s62, 31
	v_lshl_add_u64 v[130:131], s[0:1], 0, v[160:161]
	v_or_b32_e32 v133, s62, v132
	v_lshl_add_u64 v[130:131], s[62:63], 2, v[130:131]
	v_lshlrev_b32_e32 v160, 2, v132
	v_lshl_add_u64 v[130:131], v[130:131], 0, v[160:161]
	v_ashrrev_i32_e32 v132, 9, v129
	v_cndmask_b32_e32 v134, 0, v133, vcc
	s_movk_i32 s14, 0x1600
	v_mov_b32_e32 v133, s45
	v_mad_i32_i24 v132, v132, s14, v134
	v_cndmask_b32_e32 v131, v131, v133, vcc
	v_mov_b32_e32 v133, s44
	v_readlane_b32 s15, v254, 24
	v_cndmask_b32_e32 v130, v130, v133, vcc
	v_ashrrev_i32_e32 v133, 31, v132
	v_lshl_add_u32 v136, v129, 2, s15
	v_add_u32_e32 v129, 0x200, v129
	v_lshl_add_u64 v[132:133], v[132:133], 2, v[130:131]
	v_ashrrev_i32_e32 v129, 9, v129
	v_mad_i32_i24 v132, v129, s14, v134
	v_ashrrev_i32_e32 v133, 31, v132
	v_lshl_add_u64 v[130:131], v[132:133], 2, v[130:131]
	s_lshl_b32 s7, s7, 2
	s_add_i32 s7, s15, s7
	v_lshl_add_u32 v160, v128, 2, s7
	v_mov_b32_e32 v186, v161
	v_mov_b32_e32 v224, v161
	v_cmp_lt_i32_e32 vcc, 1, v180
	v_mov_b32_dpp v186, v186 row_ror:1 row_mask:0xf bank_mask:0xf
	v_mov_b32_dpp v224, v224 row_ror:2 row_mask:0xf bank_mask:0xf
	v_mov_b32_e32 v183, v186
	v_mov_b32_e32 v185, v224
	v_mov_b32_e32 v182, v186
	v_mov_b32_e32 v184, v224
	v_mov_b32_e32 v189, v186
	v_mov_b32_e32 v191, v224
	v_mov_b32_e32 v188, v186
	v_mov_b32_e32 v190, v224
	v_mov_b32_e32 v227, v186
	v_mov_b32_e32 v229, v224
	v_mov_b32_e32 v226, v186
	v_mov_b32_e32 v228, v224
	v_mov_b32_e32 v187, v186
	v_mov_b32_e32 v225, v224
	v_cmp_gt_i32_e64 s[38:39], 2, v180
	v_mov_b32_dpp v183, v124 row_shr:1 row_mask:0xf bank_mask:0xf
	v_mov_b32_dpp v185, v124 row_shr:2 row_mask:0xf bank_mask:0xf
	v_mov_b32_dpp v182, v116 row_shr:1 row_mask:0xf bank_mask:0xf
	v_mov_b32_dpp v184, v116 row_shr:2 row_mask:0xf bank_mask:0xf
	v_mov_b32_dpp v189, v125 row_shr:1 row_mask:0xf bank_mask:0xf
	v_mov_b32_dpp v191, v125 row_shr:2 row_mask:0xf bank_mask:0xf
	v_mov_b32_dpp v188, v117 row_shr:1 row_mask:0xf bank_mask:0xf
	v_mov_b32_dpp v190, v117 row_shr:2 row_mask:0xf bank_mask:0xf
	v_mov_b32_dpp v227, v126 row_shr:1 row_mask:0xf bank_mask:0xf
	v_mov_b32_dpp v229, v126 row_shr:2 row_mask:0xf bank_mask:0xf
	v_mov_b32_dpp v226, v118 row_shr:1 row_mask:0xf bank_mask:0xf
	v_mov_b32_dpp v228, v118 row_shr:2 row_mask:0xf bank_mask:0xf
	v_mov_b32_dpp v187, v127 row_shr:1 row_mask:0xf bank_mask:0xf
	v_mov_b32_dpp v225, v127 row_shr:2 row_mask:0xf bank_mask:0xf
	v_mov_b32_dpp v186, v119 row_shr:1 row_mask:0xf bank_mask:0xf
	v_mov_b32_dpp v224, v119 row_shr:2 row_mask:0xf bank_mask:0xf
	s_waitcnt vmcnt(8)
	ds_write2st64_b32 v136, v241, v235 offset1:8
	s_waitcnt lgkmcnt(0)
	s_barrier
	ds_read_b128 v[148:151], v160
	ds_read_b128 v[152:155], v160 offset:512
	ds_read_b128 v[156:159], v160 offset:1024
	ds_read_b128 v[144:147], v160 offset:1536
	ds_read_b128 v[128:131], v160 offset:2048
	ds_read_b128 v[132:135], v160 offset:2560
	ds_read_b128 v[140:143], v160 offset:3072
	ds_read_b128 v[136:139], v160 offset:3584
	s_waitcnt lgkmcnt(4)
	v_mov_b32_e32 v201, v144
	s_waitcnt lgkmcnt(3)
	v_mov_b32_e32 v202, v128
	v_mov_b32_e32 v203, v148
	s_waitcnt lgkmcnt(2)
	v_mov_b32_e32 v204, v132
	s_waitcnt lgkmcnt(0)
	v_mov_b32_e32 v200, v136
	v_mov_b32_e32 v205, v152
	v_mov_b32_e32 v206, v140
	v_mov_b32_e32 v207, v156
	v_mov_b32_e32 v198, v137
	v_mov_b32_e32 v199, v145
	v_mov_b32_e32 v196, v129
	v_mov_b32_e32 v197, v149
	v_mov_b32_e32 v194, v133
	v_mov_b32_e32 v195, v153
	v_mov_b32_e32 v192, v141
	v_mov_b32_e32 v193, v157
	v_mov_b32_e32 v216, v138
	v_mov_b32_e32 v217, v146
	v_mov_b32_e32 v218, v130
	v_mov_b32_e32 v219, v150
	v_mov_b32_e32 v220, v134
	v_mov_b32_e32 v221, v154
	v_mov_b32_e32 v222, v142
	v_mov_b32_e32 v223, v158
	v_mov_b32_e32 v214, v139
	v_mov_b32_e32 v215, v147
	v_mov_b32_e32 v212, v131
	v_mov_b32_e32 v213, v151
	v_mov_b32_e32 v210, v135
	v_mov_b32_e32 v211, v155
	v_mov_b32_e32 v208, v143
	v_mov_b32_e32 v209, v159
	s_and_saveexec_b64 s[14:15], s[38:39]
	s_xor_b64 s[40:41], exec, s[14:15]
	s_cbranch_execz .LBB0_830
	v_mov_b32_e32 v208, v143
	v_mov_b32_e32 v210, v135
	v_mov_b32_e32 v212, v131
	v_mov_b32_e32 v214, v139
	v_mov_b32_e32 v143, v158
	v_mov_b32_e32 v135, v154
	v_mov_b32_e32 v131, v150
	v_mov_b32_e32 v139, v146
	v_mov_b32_e32 v192, v141
	v_mov_b32_e32 v194, v133
	v_mov_b32_e32 v196, v129
	v_mov_b32_e32 v198, v137
	v_mov_b32_e32 v141, v156
	v_mov_b32_e32 v133, v152
	v_mov_b32_e32 v129, v148
	v_mov_b32_e32 v137, v144
	v_mov_b32_e32 v209, v159
	v_mov_b32_e32 v211, v155
	v_mov_b32_e32 v213, v151
	v_mov_b32_e32 v215, v147
	v_mov_b32_e32 v193, v157
	v_mov_b32_e32 v195, v153
	v_mov_b32_e32 v197, v149
	v_mov_b32_e32 v199, v145
	v_mov_b64_e32 v[222:223], v[142:143]
	v_mov_b64_e32 v[220:221], v[134:135]
	v_mov_b64_e32 v[218:219], v[130:131]
	v_mov_b64_e32 v[216:217], v[138:139]
	v_mov_b64_e32 v[206:207], v[140:141]
	v_mov_b64_e32 v[204:205], v[132:133]
	v_mov_b64_e32 v[202:203], v[128:129]
	v_mov_b64_e32 v[200:201], v[136:137]
